# MLA fast loop: group-B max/threshold check and group-A loop counters moved into the LDS-store drain shadow before the barrier; redundant vmcnt waits dropped
# speedup vs baseline: 1.0014x; 1.0014x over previous
; #define LAS __attribute__((address_space(3)))
; template <int DQ>
; DI void attn_item(const Frame& F, const AttnItem& it, const LAS float* rpb_lds) {
;     ...
;     auto lstore = [&](int ti) {
;         LAS unsigned char* kb = base + (ti & 1) * KBYTES; LAS unsigned char* vb = base + 2 * KBYTES + (ti % 3) * VBYTES;
; #pragma unroll
;         for (int i = 0; i < 2; ++i) { const int id = tid + i * NT; *(LAS u32x4*)(kb + ((id >> 4) * KP + (id & 15) * 8) * 2) = rk[i];
;             *(LAS u32x4*)(vb + ((id >> 3) * VP + (id & 7) * 8) * 2) = rv[i]; }
;         if (DQ == 192) *(LAS u32x4*)(kb + ((tid >> 3) * KP + 128 + (tid & 7) * 8) * 2) = rr;
;     };
;     ...
;     auto qk = [&](int ti) {
;         if (!active(ti)) return;
;         const int krow_l = (qq & 3) + 4 * ((qq >> 3) & 1) + 8 * ((qq >> 2) & 1) + 16 * (qq >> 4);
;         LAS unsigned char* kb = base + (ti & 1) * KBYTES + (krow_l * KP + 8 * hh) * 2;
; #pragma unroll
;         for (int blk = 0; blk < 2; ++blk)
; #pragma unroll
;             for (int i = 0; i < 16; ++i) s[blk][i] = 0.f;
;         bf16x8 kf[3][2];
; #pragma unroll
;         for (int p = 0; p < 2; ++p)
; #pragma unroll
;             for (int blk = 0; blk < 2; ++blk) kf[p][blk] = *(const LAS bf16x8*)(kb + (32 * blk * KP + 16 * p) * 2);
; #pragma unroll
;         for (int ks = 0; ks < KS; ++ks) {
;             if (ks + 2 < KS) {
; #pragma unroll
;                 for (int blk = 0; blk < 2; ++blk) kf[(ks + 2) % 3][blk] = *(const LAS bf16x8*)(kb + (32 * blk * KP + 16 * (ks + 2)) * 2); }
;             __builtin_amdgcn_sched_barrier(0);
; #pragma unroll
;             for (int blk = 0; blk < 2; ++blk) s[blk] = __builtin_amdgcn_mfma_f32_32x32x16_bf16(kf[ks % 3][blk], qf[ks], s[blk], 0, 0, 0);
;             __builtin_amdgcn_sched_barrier(0);
;         }
;     };
.Lfast_1347:
	s_mul_hi_u32 s4, s17, 0xaaaaaaab
	s_lshr_b32 s4, s4, 1
	s_mul_i32 s4, s4, 0xd800
	s_and_b32 s12, 1, s18
	v_subrev_u32_e32 v180, s4, v213
	v_subrev_u32_e32 v181, s4, v214
	s_cselect_b32 s4, 0x6400, 0
	v_add_u32_e32 v182, s4, v212
	ds_read_b128 v[80:83], v182 offset:12800
	ds_read_b128 v[84:87], v182
	ds_read_b128 v[176:179], v182 offset:32
	ds_read_b128 v[218:221], v182 offset:12832
	ds_read_b128 v[222:225], v182 offset:64
	ds_read_b128 v[226:229], v182 offset:12864
	s_waitcnt lgkmcnt(4)
	v_mfma_f32_32x32x16_bf16 v[96:111], v[84:87], v[144:147], 0
	v_mfma_f32_32x32x16_bf16 v[80:95], v[80:83], v[144:147], 0
	ds_read_b128 v[230:233], v182 offset:96
	ds_read_b128 v[234:237], v182 offset:12896
	s_waitcnt lgkmcnt(4)
	v_mfma_f32_32x32x16_bf16 v[96:111], v[176:179], v[140:143], v[96:111]
	v_mfma_f32_32x32x16_bf16 v[80:95], v[218:221], v[140:143], v[80:95]
	ds_read_b128 v[176:179], v182 offset:128
	ds_read_b128 v[218:221], v182 offset:12928
	s_waitcnt lgkmcnt(4)
	v_mfma_f32_32x32x16_bf16 v[96:111], v[222:225], v[136:139], v[96:111]
	v_mfma_f32_32x32x16_bf16 v[80:95], v[226:229], v[136:139], v[80:95]
	ds_read_b128 v[222:225], v182 offset:160
	ds_read_b128 v[226:229], v182 offset:12960
	s_waitcnt lgkmcnt(4)
	v_mfma_f32_32x32x16_bf16 v[96:111], v[230:233], v[132:135], v[96:111]
	v_mfma_f32_32x32x16_bf16 v[80:95], v[234:237], v[132:135], v[80:95]
	ds_read_b128 v[230:233], v182 offset:192
	ds_read_b128 v[234:237], v182 offset:12992
	s_waitcnt lgkmcnt(4)
	v_mfma_f32_32x32x16_bf16 v[96:111], v[176:179], v[128:131], v[96:111]
	v_mfma_f32_32x32x16_bf16 v[80:95], v[218:221], v[128:131], v[80:95]
	ds_read_b128 v[176:179], v182 offset:224
	ds_read_b128 v[218:221], v182 offset:13024
	s_waitcnt lgkmcnt(4)
	v_mfma_f32_32x32x16_bf16 v[96:111], v[222:225], v[124:127], v[96:111]
	v_mfma_f32_32x32x16_bf16 v[80:95], v[226:229], v[124:127], v[80:95]
	ds_read_b128 v[222:225], v182 offset:256
	ds_read_b128 v[226:229], v182 offset:13056
	s_waitcnt lgkmcnt(4)
	v_mfma_f32_32x32x16_bf16 v[96:111], v[230:233], v[120:123], v[96:111]
	v_mfma_f32_32x32x16_bf16 v[80:95], v[234:237], v[120:123], v[80:95]
	ds_read_b128 v[230:233], v182 offset:288
	ds_read_b128 v[234:237], v182 offset:13088
	s_waitcnt lgkmcnt(4)
	v_mfma_f32_32x32x16_bf16 v[96:111], v[176:179], v[116:119], v[96:111]
	v_mfma_f32_32x32x16_bf16 v[80:95], v[218:221], v[116:119], v[80:95]
	ds_read_b128 v[176:179], v182 offset:320
	ds_read_b128 v[218:221], v182 offset:13120
	s_waitcnt lgkmcnt(4)
	v_mfma_f32_32x32x16_bf16 v[96:111], v[222:225], v[112:115], v[96:111]
	v_mfma_f32_32x32x16_bf16 v[80:95], v[226:229], v[112:115], v[80:95]
	ds_read_b128 v[222:225], v182 offset:352
	ds_read_b128 v[226:229], v182 offset:13152
	s_waitcnt lgkmcnt(0)
	v_mfma_f32_32x32x16_bf16 v[96:111], v[230:233], v[10:13], v[96:111]
	v_mfma_f32_32x32x16_bf16 v[80:95], v[234:237], v[10:13], v[80:95]
	v_mfma_f32_32x32x16_bf16 v[96:111], v[176:179], v[6:9], v[96:111]
	v_mfma_f32_32x32x16_bf16 v[80:95], v[218:221], v[6:9], v[80:95]
	v_mfma_f32_32x32x16_bf16 v[96:111], v[222:225], v[2:5], v[96:111]
	v_mfma_f32_32x32x16_bf16 v[80:95], v[226:229], v[2:5], v[80:95]
	s_andn2_b64 vcc, exec, s[8:9]
	s_cbranch_vccnz .Lfast_1353
	s_cmp_eq_u32 s12, 1
	s_cselect_b32 s6, 0, 0x6400
	v_add_u32_e32 v176, s6, v209
	s_waitcnt vmcnt(0)
	ds_write_b128 v176, v[164:167]
	ds_write_b128 v181, v[160:163]
	v_add_u32_e32 v160, s6, v210
	ds_write_b128 v160, v[156:159]
	ds_write_b128 v180, v[152:155]
	v_add_u32_e32 v152, s6, v211
	s_cmp_ge_u32 s18, s3
	s_mov_b64 s[6:7], -1
	ds_write_b128 v152, v[148:151]
	s_cbranch_scc0 .Lfast_1350
	s_add_i32 s6, s15, s19
	s_add_i32 s13, s6, 0xfffff000
	s_mov_b64 s[6:7], 0

; DI float shx(float v, int m, int lane) { return __builtin_bit_cast(float, __builtin_amdgcn_ds_bpermute((lane ^ m) << 2, __builtin_bit_cast(int, v))); }
; template <int DQ>
; DI void attn_item(const Frame& F, const AttnItem& it, const LAS float* rpb_lds) {
;     ...
;     auto gload = [&](int ti) {
;         int rowb, vcol;
;         if (ti < it.ntl) { const int kt = it.t0 + ti; rowb = it.lat_row0 + kt * 64; vcol = kt * 64; } else { const int j = ti - it.ntl; rowb = it.ctx_row0 + j * 64; vcol = SEQ + j * 64; }
; #pragma unroll
;         for (int i = 0; i < 2; ++i) { const int id = tid + i * NT; rk[i] = *(const u32x4*)(it.kn + (size_t)(rowb + (id >> 4)) * it.ldk + (id & 15) * 8);
;             rv[i] = *(const u32x4*)(it.vt + (size_t)(id >> 3) * KEYS + vcol + (id & 7) * 8); }
;         if (DQ == 192) rr = *(const u32x4*)(it.kr + (size_t)(rowb + (tid >> 3)) * UC + (tid & 7) * 8);
;     };
;     ...
;         float mx = s[0][0];
; #pragma unroll
;         for (int blk = 0; blk < 2; ++blk)
; #pragma unroll
;             for (int i = 0; i < 16; ++i) mx = fmaxf(mx, s[blk][i]);
;         mx = fmaxf(mx, shx(mx, 32, lane));
;         const float mnew = fmaxf(mrun, mx), alpha = __builtin_amdgcn_exp2f(mrun - mnew);
.Lfast_1352:
	s_ashr_i32 s7, s6, 31
	s_lshl_b64 s[6:7], s[6:7], 1
	s_lshl_b32 s98, s13, 11
	s_mov_b32 s99, 0
	s_mul_i32 s100, s13, 0x1a00
	s_mov_b32 s101, 0
	v_lshl_add_u64 v[148:149], v[198:199], 0, s[100:101]
	v_lshl_add_u64 v[152:153], v[170:171], 0, s[6:7]
	v_lshl_add_u64 v[156:157], v[196:197], 0, s[98:99]
	v_lshl_add_u64 v[160:161], v[168:169], 0, s[6:7]
	v_lshl_add_u64 v[164:165], v[194:195], 0, s[98:99]
	global_load_dwordx4 v[148:151], v[148:149], off
	s_nop 0
	global_load_dwordx4 v[152:155], v[152:153], off
	s_nop 0
	global_load_dwordx4 v[156:159], v[156:157], off
	s_nop 0
	global_load_dwordx4 v[160:163], v[160:161], off
	s_nop 0
	global_load_dwordx4 v[164:167], v[164:165], off
	v_max_f32_e32 v176, v97, v97
	v_max_f32_e32 v177, v96, v96
	v_max_f32_e32 v176, v177, v176
	v_max3_f32 v176, v176, v98, v99
	v_max3_f32 v176, v176, v100, v101
	v_max3_f32 v176, v176, v102, v103
	v_max3_f32 v176, v176, v104, v105
	v_max3_f32 v176, v176, v106, v107
	v_max3_f32 v176, v176, v108, v109
	v_max3_f32 v176, v176, v110, v111
	v_max3_f32 v176, v176, v80, v81
	v_max3_f32 v176, v176, v82, v83
	v_max3_f32 v176, v176, v84, v85
	v_max3_f32 v176, v176, v86, v87
	v_max3_f32 v176, v176, v88, v89
	v_max3_f32 v176, v176, v90, v91
	v_max3_f32 v176, v176, v92, v93
	v_max3_f32 v176, v176, v94, v95
	v_cmp_lt_f32_e32 vcc, 0x42000000, v176
	v_cmp_gt_f32_e64 s[98:99], s32, v176
	s_nop 1
	s_or_b64 vcc, vcc, s[98:99]
	s_waitcnt lgkmcnt(0)
	s_barrier
	s_cbranch_vccz .Lfast_1355
	s_branch .Lfast_stub

; #define LAS __attribute__((address_space(3)))
; template <int DQ>
; DI void attn_item(const Frame& F, const AttnItem& it, const LAS float* rpb_lds) {
;     ...
;     auto lstore = [&](int ti) {
;         LAS unsigned char* kb = base + (ti & 1) * KBYTES; LAS unsigned char* vb = base + 2 * KBYTES + (ti % 3) * VBYTES;
; #pragma unroll
;         for (int i = 0; i < 2; ++i) { const int id = tid + i * NT; *(LAS u32x4*)(kb + ((id >> 4) * KP + (id & 15) * 8) * 2) = rk[i];
;             *(LAS u32x4*)(vb + ((id >> 3) * VP + (id & 7) * 8) * 2) = rv[i]; }
;         if (DQ == 192) *(LAS u32x4*)(kb + ((tid >> 3) * KP + 128 + (tid & 7) * 8) * 2) = rr;
;     };
;     ...
;         const float mnew = fmaxf(mrun, mx), alpha = __builtin_amdgcn_exp2f(mrun - mnew);
;         mrun = mnew;
;         float ps = 0.f;
; #pragma unroll
;         for (int blk = 0; blk < 2; ++blk)
; #pragma unroll
;             for (int i = 0; i < 16; ++i) { const float p = __builtin_amdgcn_exp2f(s[blk][i] - mnew); s[blk][i] = p; ps += p; }
;         lrun = lrun * alpha + ps;
;         if (__builtin_amdgcn_ballot_w64(alpha != 1.f) != 0ull) {
; #pragma unroll
;             for (int db = 0; db < 4; ++db)
; #pragma unroll
;                 for (int i = 0; i < 16; ++i) o[db][i] *= alpha;
;         }
;         LAS unsigned char* vq = vb + (qq * VP + 8 * hh) * 2;
;         auto vload = [&](int step, int db) { return *(const LAS bf16x8*)(vq + (32 * db * VP + 16 * step) * 2); };
;         bf16x8 vf[2][4];
; #pragma unroll
;         for (int db = 0; db < 4; ++db) vf[0][db] = vload(0, db);
; #pragma unroll
;         for (int st = 0; st < 4; ++st) {
;             if (st + 1 < 4) {
; #pragma unroll
;                 for (int db = 0; db < 4; ++db) vf[(st + 1) & 1][db] = vload(st + 1, db); }
;             __builtin_amdgcn_sched_barrier(0);
;             const int blk = st >> 1, s2 = st & 1;
;             u32x4 pw; pw.x = pk2(s[blk][8 * s2], s[blk][8 * s2 + 1]); pw.y = pk2(s[blk][8 * s2 + 2], s[blk][8 * s2 + 3]);
;             pw.z = pk2(s[blk][8 * s2 + 4], s[blk][8 * s2 + 5]); pw.w = pk2(s[blk][8 * s2 + 6], s[blk][8 * s2 + 7]);
;             const bf16x8 pf = __builtin_bit_cast(bf16x8, pw);
; #pragma unroll
;             for (int db = 0; db < 4; ++db) o[db] = __builtin_amdgcn_mfma_f32_32x32x16_bf16(vf[st & 1][db], pf, o[db], 0, 0, 0);
;             __builtin_amdgcn_sched_barrier(0);
;         }
.Lfast_stub:
	v_add_u32_e32 v218, 0, v181
	v_add_u32_e32 v205, 0, v180
	v_cndmask_b32_e64 v176, 0, 1, s[8:9]
	v_cmp_ne_u32_e64 s[4:5], 1, v176
	s_cmp_eq_u32 s32, 0xc2000000
	s_cselect_b32 s98, 0xff800000, 0
	v_mov_b32_e32 v174, s98
	s_branch .LBB0_1353
.Lfast_1355:
	s_mul_hi_u32 s6, s16, 0xaaaaaaab
	s_lshr_b32 s6, s6, 1
	s_mul_i32 s6, s6, 0xd800
	v_subrev_u32_e32 v183, s6, v215
	ds_read_b128 v[176:179], v183 offset:4608
	ds_read_b128 v[220:223], v183 offset:9216
	ds_read_b128 v[224:227], v183 offset:13824
	ds_read_b128 v[228:231], v183
	ds_read_b128 v[232:235], v183 offset:32
	ds_read_b128 v[236:239], v183 offset:4640
	ds_read_b128 v[240:243], v183 offset:9248
	ds_read_b128 v[244:247], v183 offset:13856
	v_exp_f32_e32 v96, v96
	v_exp_f32_e32 v97, v97
	v_exp_f32_e32 v98, v98
	v_exp_f32_e32 v99, v99
	v_exp_f32_e32 v100, v100
	v_exp_f32_e32 v101, v101
	v_exp_f32_e32 v102, v102
	v_exp_f32_e32 v103, v103
	v_cvt_pk_bf16_f32 v248, v96, v97
	v_cvt_pk_bf16_f32 v249, v98, v99
	v_cvt_pk_bf16_f32 v250, v100, v101
	v_cvt_pk_bf16_f32 v251, v102, v103
	s_waitcnt lgkmcnt(4)
	s_nop 0
	v_mfma_f32_32x32x16_bf16 v[64:79], v[228:231], v[248:251], v[64:79]
	v_exp_f32_e32 v104, v104
	v_exp_f32_e32 v105, v105
	v_mfma_f32_32x32x16_bf16 v[48:63], v[176:179], v[248:251], v[48:63]
	v_exp_f32_e32 v106, v106
	v_exp_f32_e32 v107, v107
	v_mfma_f32_32x32x16_bf16 v[32:47], v[220:223], v[248:251], v[32:47]
	v_exp_f32_e32 v108, v108
	v_exp_f32_e32 v109, v109
	v_mfma_f32_32x32x16_bf16 v[16:31], v[224:227], v[248:251], v[16:31]
	v_exp_f32_e32 v110, v110
	v_exp_f32_e32 v111, v111
	ds_read_b128 v[176:179], v183 offset:64
	ds_read_b128 v[220:223], v183 offset:4672
	ds_read_b128 v[224:227], v183 offset:9280
	ds_read_b128 v[228:231], v183 offset:13888
	v_cvt_pk_bf16_f32 v248, v104, v105
	v_cvt_pk_bf16_f32 v249, v106, v107
	v_cvt_pk_bf16_f32 v250, v108, v109
	v_cvt_pk_bf16_f32 v251, v110, v111
	s_waitcnt lgkmcnt(4)
	s_nop 0
	v_mfma_f32_32x32x16_bf16 v[64:79], v[232:235], v[248:251], v[64:79]
	v_exp_f32_e32 v80, v80
	v_exp_f32_e32 v81, v81
	v_add_f32_e32 v96, v97, v96
	v_add_f32_e32 v98, v99, v98
	v_mfma_f32_32x32x16_bf16 v[48:63], v[236:239], v[248:251], v[48:63]
	v_exp_f32_e32 v82, v82
	v_exp_f32_e32 v83, v83
	v_add_f32_e32 v100, v101, v100
	v_add_f32_e32 v102, v103, v102
	v_mfma_f32_32x32x16_bf16 v[32:47], v[240:243], v[248:251], v[32:47]
	v_exp_f32_e32 v84, v84
	v_exp_f32_e32 v85, v85
	v_add_f32_e32 v96, v98, v96
	v_add_f32_e32 v100, v102, v100
	v_mfma_f32_32x32x16_bf16 v[16:31], v[244:247], v[248:251], v[16:31]
	v_exp_f32_e32 v86, v86
	v_exp_f32_e32 v87, v87
	v_add_f32_e32 v96, v100, v96
	ds_read_b128 v[232:235], v183 offset:96
	ds_read_b128 v[236:239], v183 offset:4704
	ds_read_b128 v[240:243], v183 offset:9312
	ds_read_b128 v[244:247], v183 offset:13920
	v_cvt_pk_bf16_f32 v248, v80, v81
	v_cvt_pk_bf16_f32 v249, v82, v83
	v_cvt_pk_bf16_f32 v250, v84, v85
	v_cvt_pk_bf16_f32 v251, v86, v87
	s_waitcnt lgkmcnt(4)
	s_nop 0
	v_mfma_f32_32x32x16_bf16 v[64:79], v[176:179], v[248:251], v[64:79]
	v_exp_f32_e32 v88, v88
	v_exp_f32_e32 v89, v89
	v_add_f32_e32 v104, v105, v104
	v_add_f32_e32 v106, v107, v106
	v_mfma_f32_32x32x16_bf16 v[48:63], v[220:223], v[248:251], v[48:63]
	v_exp_f32_e32 v90, v90
	v_exp_f32_e32 v91, v91
	v_add_f32_e32 v108, v109, v108
	v_add_f32_e32 v110, v111, v110
	v_mfma_f32_32x32x16_bf16 v[32:47], v[224:227], v[248:251], v[32:47]
	v_exp_f32_e32 v92, v92
	v_exp_f32_e32 v93, v93
	v_add_f32_e32 v104, v106, v104
	v_add_f32_e32 v108, v110, v108
	v_mfma_f32_32x32x16_bf16 v[16:31], v[228:231], v[248:251], v[16:31]
	v_exp_f32_e32 v94, v94
	v_exp_f32_e32 v95, v95
	v_add_f32_e32 v104, v108, v104
	v_cvt_pk_bf16_f32 v176, v88, v89
	v_cvt_pk_bf16_f32 v177, v90, v91
	v_cvt_pk_bf16_f32 v178, v92, v93
	v_cvt_pk_bf16_f32 v179, v94, v95
	s_waitcnt lgkmcnt(0)
	s_nop 0
	v_mfma_f32_32x32x16_bf16 v[64:79], v[232:235], v[176:179], v[64:79]
	v_add_f32_e32 v80, v81, v80
	v_add_f32_e32 v82, v83, v82
	v_add_f32_e32 v84, v85, v84
	v_add_f32_e32 v86, v87, v86
	v_add_f32_e32 v88, v89, v88
	v_add_f32_e32 v90, v91, v90
	v_mfma_f32_32x32x16_bf16 v[48:63], v[236:239], v[176:179], v[48:63]
	v_add_f32_e32 v92, v93, v92
	v_add_f32_e32 v94, v95, v94
	v_add_f32_e32 v80, v82, v80
	v_add_f32_e32 v84, v86, v84
	v_add_f32_e32 v88, v90, v88
	v_add_f32_e32 v92, v94, v92
	v_mfma_f32_32x32x16_bf16 v[32:47], v[240:243], v[176:179], v[32:47]
	v_add_f32_e32 v80, v84, v80
	v_add_f32_e32 v88, v92, v88
	v_add_f32_e32 v96, v104, v96
	v_mfma_f32_32x32x16_bf16 v[16:31], v[244:247], v[176:179], v[16:31]
	v_add_f32_e32 v80, v88, v80
	v_add_f32_e32 v96, v80, v96
	s_andn2_b64 vcc, exec, s[10:11]
	s_cbranch_vccnz .Lfast_1361
	s_cmp_eq_u32 s12, 1
	s_cselect_b32 s12, 0, 0x6400
	v_add_u32_e32 v176, s12, v209
	s_waitcnt vmcnt(0)
	ds_write_b128 v176, v[164:167]
	ds_write_b128 v181, v[160:163]
	v_add_u32_e32 v160, s12, v210
	ds_write_b128 v160, v[156:159]
	ds_write_b128 v180, v[152:155]
	v_add_u32_e32 v152, s12, v211
	s_cmp_ge_u32 s18, s3
	s_mov_b64 s[12:13], -1
	ds_write_b128 v152, v[148:151]
	s_cbranch_scc0 .Lfast_1358
	s_add_i32 s12, s15, s19
	s_add_i32 s21, s12, 0xfffff000
	s_mov_b64 s[12:13], 0

; template <int DQ>
; DI void attn_item(const Frame& F, const AttnItem& it, const LAS float* rpb_lds) {
;     ...
;     auto gload = [&](int ti) {
;         int rowb, vcol;
;         if (ti < it.ntl) { const int kt = it.t0 + ti; rowb = it.lat_row0 + kt * 64; vcol = kt * 64; } else { const int j = ti - it.ntl; rowb = it.ctx_row0 + j * 64; vcol = SEQ + j * 64; }
; #pragma unroll
;         for (int i = 0; i < 2; ++i) { const int id = tid + i * NT; rk[i] = *(const u32x4*)(it.kn + (size_t)(rowb + (id >> 4)) * it.ldk + (id & 15) * 8);
;             rv[i] = *(const u32x4*)(it.vt + (size_t)(id >> 3) * KEYS + vcol + (id & 7) * 8); }
;         if (DQ == 192) rr = *(const u32x4*)(it.kr + (size_t)(rowb + (tid >> 3)) * UC + (tid & 7) * 8);
;     };
;     ...
;     for (int ti = 0; ti < ntile; ++ti) {
;         qk(ti);
;         if (grpB) { if (ti + 1 < ntile) lstore(ti + 1); if (ti + 2 < ntile) gload(ti + 2); __syncthreads(); }
;         smpv(ti);
;         if (!grpB) { if (ti + 1 < ntile) lstore(ti + 1); if (ti + 2 < ntile) gload(ti + 2); __syncthreads(); }
.Lfast_1360:
	s_ashr_i32 s13, s12, 31
	s_lshl_b64 s[12:13], s[12:13], 1
	s_lshl_b32 s98, s21, 11
	s_mov_b32 s99, 0
	s_mul_i32 s100, s21, 0x1a00
	s_mov_b32 s101, 0
	v_lshl_add_u64 v[148:149], v[198:199], 0, s[100:101]
	v_lshl_add_u64 v[152:153], v[170:171], 0, s[12:13]
	v_lshl_add_u64 v[156:157], v[196:197], 0, s[98:99]
	v_lshl_add_u64 v[160:161], v[168:169], 0, s[12:13]
	v_lshl_add_u64 v[164:165], v[194:195], 0, s[98:99]
	global_load_dwordx4 v[148:151], v[148:149], off
	s_nop 0
	global_load_dwordx4 v[152:155], v[152:153], off
	s_nop 0
	global_load_dwordx4 v[156:159], v[156:157], off
	s_nop 0
	global_load_dwordx4 v[160:163], v[160:161], off
	s_nop 0
	global_load_dwordx4 v[164:167], v[164:165], off
	s_add_i32 s18, s18, 1
	s_add_i32 s19, s19, 64
	s_add_i32 s17, s17, 1
	s_add_i32 s12, s20, s18
	s_add_i32 s16, s16, 1
	v_add_f32_e32 v216, v216, v96
	v_add_u32_e32 v213, 0x4800, v213
	v_add_u32_e32 v214, 0x4800, v214
	s_cmp_lg_u32 s12, 4
	v_add_u32_e32 v215, 0x4800, v215
	s_waitcnt lgkmcnt(0)
	s_barrier
	s_cbranch_scc0 .Lfast_exit
	s_mov_b32 s32, 0xff800000
	s_branch .Lfast_1347
